# v72 with the hoisted gate / normaliser loads restricted to waves 0 and 1 (no redundant loads from the other six waves)
# baseline (speedup 1.0000x reference)
.LBB0_1049:
	s_or_b32 s33, s24, s72
	s_lshl_b32 s0, s33, 7
	s_or_b32 s68, s18, s0
	s_or_b32 s0, s33, s28
	s_ashr_i32 s1, s0, 31
	s_lshl_b64 s[0:1], s[0:1], 2
	s_add_u32 s0, s73, s0
	s_addc_u32 s1, s74, s1
	v_mov_b32_e32 v4, v0
	global_load_dword v211, v3, s[0:1]
	s_mov_b32 s69, s19
	s_and_b64 vcc, exec, s[88:89]
	s_cbranch_vccz .Lmy_p4_nog
	v_and_b32_e32 v222, 63, v4
	v_lshl_or_b32 v224, v222, 1, s68
	v_mov_b32_e32 v225, s69
	v_lshlrev_b64 v[224:225], 5, v[224:225]
	v_lshl_add_u64 v[224:225], s[64:65], 0, v[224:225]
	global_load_dword v226, v[224:225], off offset:48
	global_load_dword v227, v[224:225], off offset:16
	global_load_dword v228, v[224:225], off offset:32
	global_load_dword v229, v[224:225], off
.Lmy_p4_nog:
	s_and_b64 vcc, exec, s[90:91]
	s_cbranch_vccz .Lmy_p4_non
	s_or_b32 s0, s33, s29
	s_ashr_i32 s1, s0, 31
	s_lshl_b64 s[0:1], s[0:1], 10
	s_add_u32 s0, s77, s0
	s_addc_u32 s1, s78, s1
	v_and_b32_e32 v222, 63, v4
	v_lshlrev_b32_e32 v223, 2, v222
	global_load_dword v230, v223, s[0:1]
	global_load_dword v231, v223, s[0:1] offset:256
	global_load_dword v232, v223, s[0:1] offset:512
	global_load_dword v233, v223, s[0:1] offset:768
.Lmy_p4_non:
	s_waitcnt vmcnt(17)
	v_ashrrev_i32_e32 v70, 5, v4
	v_ashrrev_i32_e32 v71, 31, v70
	v_lshlrev_b32_e32 v2, 4, v4
	v_lshl_add_u64 v[6:7], s[68:69], 0, v[70:71]
	v_and_b32_e32 v2, 0x1f0, v2
	v_lshl_add_u64 v[8:9], s[20:21], 0, v[2:3]
	v_lshlrev_b64 v[6:7], 11, v[6:7]
	v_lshl_add_u64 v[62:63], v[8:9], 0, v[6:7]
	v_lshl_add_u64 v[10:11], s[36:37], 0, v[2:3]
	v_add_co_u32_e32 v14, vcc, s80, v62
	v_lshl_add_u64 v[64:65], v[10:11], 0, v[6:7]
	s_nop 0
	v_addc_co_u32_e32 v15, vcc, 0, v63, vcc
	v_add_co_u32_e32 v18, vcc, s80, v64
	global_load_dwordx4 v[6:9], v[62:63], off
	global_load_dwordx4 v[10:13], v[64:65], off
	v_addc_co_u32_e32 v19, vcc, 0, v65, vcc
	v_add_co_u32_e32 v22, vcc, s46, v62
	global_load_dwordx4 v[14:17], v[14:15], off
	s_nop 0
	global_load_dwordx4 v[18:21], v[18:19], off
	v_addc_co_u32_e32 v23, vcc, 0, v63, vcc
	v_add_co_u32_e32 v26, vcc, s46, v64
	s_movk_i32 s0, 0x210
	s_nop 0
	v_addc_co_u32_e32 v27, vcc, 0, v65, vcc
	v_add_co_u32_e32 v30, vcc, s81, v62
	global_load_dwordx4 v[22:25], v[22:23], off
	s_nop 0
	global_load_dwordx4 v[26:29], v[26:27], off
	v_addc_co_u32_e32 v31, vcc, 0, v63, vcc
	v_add_co_u32_e32 v34, vcc, s81, v64
	v_mul_lo_u32 v5, v70, s0
	s_nop 0
	v_addc_co_u32_e32 v35, vcc, 0, v65, vcc
	v_add_co_u32_e32 v38, vcc, s47, v62
	global_load_dwordx4 v[30:33], v[30:31], off
	s_nop 0
	global_load_dwordx4 v[34:37], v[34:35], off
	v_addc_co_u32_e32 v39, vcc, 0, v63, vcc
	v_add_co_u32_e32 v42, vcc, s47, v64
	v_add3_u32 v2, v5, v2, 0
	s_nop 0
	v_addc_co_u32_e32 v43, vcc, 0, v65, vcc
	v_add_co_u32_e32 v46, vcc, s82, v62
	global_load_dwordx4 v[38:41], v[38:39], off
	s_nop 0
	global_load_dwordx4 v[42:45], v[42:43], off
	v_addc_co_u32_e32 v47, vcc, 0, v63, vcc
	v_add_co_u32_e32 v50, vcc, s82, v64
	v_add_u32_e32 v5, 0x10800, v2
	s_nop 0
	v_addc_co_u32_e32 v51, vcc, 0, v65, vcc
	v_add_co_u32_e32 v54, vcc, s83, v62
	global_load_dwordx4 v[46:49], v[46:47], off
	s_nop 0
	global_load_dwordx4 v[50:53], v[50:51], off
	v_addc_co_u32_e32 v55, vcc, 0, v63, vcc
	v_add_co_u32_e32 v58, vcc, s83, v64
	s_cmp_lg_u32 s33, 0
	s_nop 0
	v_addc_co_u32_e32 v59, vcc, 0, v65, vcc
	v_add_co_u32_e32 v62, vcc, s84, v62
	global_load_dwordx4 v[54:57], v[54:55], off
	s_nop 0
	global_load_dwordx4 v[58:61], v[58:59], off
	v_addc_co_u32_e32 v63, vcc, 0, v63, vcc
	v_add_co_u32_e32 v66, vcc, s84, v64
	s_cselect_b64 s[24:25], -1, 0
	s_nop 0
	v_addc_co_u32_e32 v67, vcc, 0, v65, vcc
	global_load_dwordx4 v[62:65], v[62:63], off
	s_nop 0
	global_load_dwordx4 v[66:69], v[66:67], off
	s_cmp_eq_u32 s33, 0
	s_cbranch_scc1 .Lmy_p4_noct
	s_or_b32 s0, s33, s29
	s_ashr_i32 s1, s0, 31
	s_lshl_b64 s[0:1], s[0:1], 17
	s_add_u32 s0, s75, s0
	s_addc_u32 s1, s76, s1
	v_and_b32_e32 v216, 63, v4
	v_lshlrev_b32_e32 v216, 4, v216
	v_mov_b32_e32 v217, 0
	v_lshl_add_u64 v[218:219], s[0:1], 0, v[216:217]
	v_lshl_add_u64 v[218:219], v[218:219], 0, s[38:39]
	s_movk_i32 s0, 0x1000
	v_add_co_u32_e32 v220, vcc, s0, v218
	global_load_dwordx4 v[84:87], v[218:219], off
	global_load_dwordx4 v[88:91], v[218:219], off offset:1024
	global_load_dwordx4 v[92:95], v[218:219], off offset:2048
	global_load_dwordx4 v[96:99], v[218:219], off offset:3072
	v_addc_co_u32_e32 v221, vcc, 0, v219, vcc
	global_load_dwordx4 v[100:103], v[220:221], off
	global_load_dwordx4 v[104:107], v[220:221], off offset:1024
	global_load_dwordx4 v[108:111], v[220:221], off offset:2048
	global_load_dwordx4 v[112:115], v[220:221], off offset:3072
	v_add_co_u32_e32 v220, vcc, 0x2000, v218
	s_nop 1
	v_addc_co_u32_e32 v221, vcc, 0, v219, vcc
	v_add_co_u32_e32 v218, vcc, 0x3000, v218
	global_load_dwordx4 v[116:119], v[220:221], off
	global_load_dwordx4 v[120:123], v[220:221], off offset:1024
	global_load_dwordx4 v[124:127], v[220:221], off offset:2048
	global_load_dwordx4 v[128:131], v[220:221], off offset:3072
	v_addc_co_u32_e32 v219, vcc, 0, v219, vcc
	global_load_dwordx4 v[132:135], v[218:219], off
	global_load_dwordx4 v[136:139], v[218:219], off offset:1024
	global_load_dwordx4 v[140:143], v[218:219], off offset:2048
	global_load_dwordx4 v[144:147], v[218:219], off offset:3072
